# combined: FFN-up epilogue row-scale table reads batched + mixer-A far loop without the lagged-PV wave stagger (on top of exact vmcnt(24) transitions)
# speedup vs baseline: 1.0042x; 1.0042x over previous
; template <int MODE, int NQ, int TS, bool FAST = false> ...
;     ...
;   const int kkey_ = wave * 8 + (lane >> 3);
;   const bf16_t* kg = proj + (size_t)(seq_base + TS * kkey_) * ld + koff + (((lane & 7) ^ ((kkey_ >> 1) & 7)) * 8);
;   const bf16_t* vg = proj + (size_t)(seq_base + TS * ((wave & 3) * 16 + (lane >> 2))) * ld + voff + ((wave >> 2) * 4 + (lane & 3)) * 8;
;   const unsigned sdst = (unsigned)__builtin_amdgcn_readfirstlane(wave * 1024);
;     ...
;   const int ktl = kt1 - 1;
;   constexpr int TAB_OFF = 6 * 16384, TAB_N = (MODE == 3) ? 640 : 1024, TAB_ZERO = TAB_N / 2;
;   if (MODE == 0 || MODE == 3) {
;     float* tab = (float*)(lds + TAB_OFF);
;     for (int e = tid; e < TAB_N; e += 512) {
;       const int oo = e - TAB_ZERO, aa = oo < 0 ? -oo : oo;
;       if (MODE == 0) {
;         const int c = (aa <= 64 ? 1 : 0) + (((oo & 3) == 0 && aa <= 256) ? 1 : 0) + (((oo & 15) == 0 && aa <= 256) ? 1 : 0);
;         tab[e] = c ? (-slope2 * (float)aa + (c == 1 ? 0.f : (c == 2 ? 1.f : 1.5849625007f))) : -1e30f;
;       } else {
;         tab[e] = (aa >= 17 && aa <= 64) ? -slope2 * (float)(16 * aa) : -1e30f;
;       }
;     }
;   }
;   if (MODE == 2) {
;     float* tab = (float*)(lds + TAB_OFF) + (wave & 3) * 512;
; #pragma unroll
;     for (int i = 0; i < 4; ++i) { const int e = (wave >> 2) * 64 + lane + 128 * i; const int oo = e - 256, aa = oo < 0 ? -oo : oo; tab[e] = (aa <= 128) ? -slope2 * (float)aa : -1e30f; }
;   }
;   ATT_ISSUE(kt0, 0); ATT_ISSUE((kt0 + 1 < ktl ? kt0 + 1 : ktl), 1); ATT_ISSUE((kt0 + 2 < ktl ? kt0 + 2 : ktl), 2); ATT_ISSUE((kt0 + 3 < ktl ? kt0 + 3 : ktl), 3);
;   asm volatile("s_waitcnt vmcnt(6) lgkmcnt(0)\n\ts_barrier" ::: "memory");
;   int kfo4[4];
; #pragma unroll
;   for (int ks = 0; ks < 4; ++ks) kfo4[ks] = r32 * 128 + (((2 * ks + hh) ^ ((r32 >> 1) & 7)) << 4);
;   const int vfo = 8192 + (4 * hh + ((lane & 15) >> 2)) * 64 + ((lane >> 4) & 1) * 32 + (lane & 3) * 8;
;   const bool g2 = wave >= 4;
;     ...
;   for (int kt = kt0; kt < kt1; ++kt) {
;     { const int tn = (kt + 4 < ktl) ? kt + 4 : ktl; int s4 = slot + 4; if (s4 >= NS) s4 -= NS; ATT_ISSUE(tn, s4); }
;     const bool act = tile_active(kt);
;     if (!g2) {
;       if (act) { QK(slot); SM(kt); PV(slot); }
;     } else {
;       if (kt > kt0 && tile_active(kt - 1)) PV(sp);
;       if (act) { QK(slot); SM(kt); }
.LBB0_266:
	s_or_b64 exec, exec, s[28:29]
	s_sub_i32 s0, s7, 64
	v_and_b32_e32 v103, 63, v2
	s_ashr_i32 s14, s0, 6
	s_add_i32 s0, s7, 0x13f
	s_lshr_b32 s0, s0, 6
	v_lshrrev_b32_e32 v0, 3, v103
	s_max_i32 s8, s14, 0
	s_or_b32 s1, s0, 1
	v_lshl_or_b32 v0, v10, 3, v0
	s_cmp_lt_u32 s0, s6
	v_lshl_add_u32 v3, v0, 4, s5
	v_mov_b64_e32 v[4:5], s[66:67]
	v_lshrrev_b32_e32 v0, 1, v0
	s_cselect_b32 s15, s1, s6
	v_mad_i64_i32 v[4:5], s[0:1], v3, s24, v[4:5]
	v_xor_b32_e32 v0, v0, v2
	s_lshl_b64 s[0:1], s[40:41], 1
	v_lshlrev_b32_e32 v0, 4, v0
	v_lshl_add_u64 v[4:5], v[4:5], 0, s[0:1]
	v_and_b32_e32 v0, 0x70, v0
	v_lshl_add_u64 v[98:99], v[4:5], 0, v[0:1]
	v_lshlrev_b32_e32 v0, 4, v10
	v_lshrrev_b32_e32 v3, 2, v103
	v_and_or_b32 v0, v0, 48, v3
	v_lshl_add_u32 v0, v0, 4, s5
	s_movk_i32 s5, 0x900
	v_mul_lo_u32 v0, v0, s5
	v_lshl_add_u64 v[4:5], v[0:1], 1, s[66:67]
	v_lshl_add_u64 v[4:5], v[4:5], 0, s[0:1]
	v_and_b32_e32 v0, 3, v2
	s_mov_b32 s0, 0x1ffffffc
	v_and_or_b32 v3, v10, s0, v0
	v_lshlrev_b32_e32 v6, 3, v3
	v_ashrrev_i32_e32 v7, 31, v6
	v_lshl_add_u64 v[100:101], v[6:7], 1, v[4:5]
	s_lshl_b32 s16, s9, 10
	v_mad_u64_u32 v[4:5], s[0:1], s8, v235, v[98:99]
	v_lshl_add_u64 v[4:5], v[4:5], 0, s[60:61]
	s_mov_b32 m0, s16
	s_add_i32 s5, s15, -1
	global_load_lds_dwordx4 v[4:5], off
	v_mad_u64_u32 v[4:5], s[0:1], s8, v235, v[100:101]
	s_add_i32 s6, s8, 1
	v_lshl_add_u64 v[4:5], v[4:5], 0, s[58:59]
	s_add_i32 m0, s16, 0x2000
	s_min_u32 s7, s6, s5
	global_load_lds_dwordx4 v[4:5], off
	v_mad_u64_u32 v[4:5], s[0:1], s7, v235, v[98:99]
	v_lshl_add_u64 v[4:5], v[4:5], 0, s[60:61]
	s_add_i32 m0, s16, 0x4000
	v_lshlrev_b32_e32 v3, 4, v2
	global_load_lds_dwordx4 v[4:5], off
	v_mad_u64_u32 v[4:5], s[0:1], s7, v235, v[100:101]
	s_add_i32 s0, s8, 2
	v_lshl_add_u64 v[4:5], v[4:5], 0, s[58:59]
	s_add_i32 m0, s16, 0x6000
	s_min_u32 s7, s0, s5
	global_load_lds_dwordx4 v[4:5], off
	v_mad_u64_u32 v[4:5], s[0:1], s7, v235, v[98:99]
	v_lshl_add_u64 v[4:5], v[4:5], 0, s[60:61]
	s_add_i32 m0, s16, 0x8000
	v_and_b32_e32 v3, 0xc0, v3
	global_load_lds_dwordx4 v[4:5], off
	v_mad_u64_u32 v[4:5], s[0:1], s7, v235, v[100:101]
	s_add_i32 s0, s8, 3
	v_lshl_add_u64 v[4:5], v[4:5], 0, s[58:59]
	s_add_i32 m0, s16, 0xa000
	s_min_u32 s7, s0, s5
	global_load_lds_dwordx4 v[4:5], off
	v_mad_u64_u32 v[4:5], s[0:1], s7, v235, v[98:99]
	v_lshl_add_u64 v[4:5], v[4:5], 0, s[60:61]
	s_add_i32 m0, s16, 0xc000
	v_lshl_or_b32 v3, v105, 8, v3
	global_load_lds_dwordx4 v[4:5], off
	v_mad_u64_u32 v[4:5], s[0:1], s7, v235, v[100:101]
	v_lshl_add_u64 v[4:5], v[4:5], 0, s[58:59]
	s_add_i32 m0, s16, 0xe000
	v_lshlrev_b32_e32 v0, 3, v0
	global_load_lds_dwordx4 v[4:5], off
	s_waitcnt vmcnt(6) lgkmcnt(0)
	s_barrier
	v_lshlrev_b32_e32 v4, 1, v2
	v_and_b32_e32 v4, 32, v4
	s_mov_b32 s9, 0
	v_or3_b32 v106, v3, v4, v0
	v_cmp_lt_i32_e64 s[36:37], 7, v10
	v_cmp_gt_i32_e64 s[38:39], 8, v10
	s_cmp_lt_i32 s14, s15
	v_subrev_u32_e32 v107, 64, v9
	v_add_u32_e32 v108, 0x5f, v9
	s_cbranch_scc0 .LBB0_271
	s_add_i32 s0, s8, 4
	s_min_u32 s7, s0, s5
	v_mad_u64_u32 v[4:5], s[0:1], s7, v235, v[98:99]
	v_lshl_add_u64 v[4:5], v[4:5], 0, s[60:61]
	s_add_i32 m0, s16, 0x10000
	v_lshrrev_b32_e32 v0, 1, v2
	global_load_lds_dwordx4 v[4:5], off
	v_mad_u64_u32 v[4:5], s[0:1], s7, v235, v[100:101]
	v_lshl_add_u64 v[4:5], v[4:5], 0, s[58:59]
	s_add_i32 m0, s16, 0x12000
	v_bfe_u32 v2, v2, 1, 3
	global_load_lds_dwordx4 v[4:5], off
	s_lshl_b32 s7, s8, 6
	v_bitop3_b32 v3, v105, v2, 6 bitop3:0x36
	v_lshlrev_b32_e32 v4, 7, v8
	v_bitop3_b32 v0, v105, v0, 7 bitop3:0x78
	s_or_b32 s0, s7, 63
	v_lshl_or_b32 v97, v3, 4, v4
	v_bitop3_b32 v3, v105, v2, 4 bitop3:0x36
	v_bitop3_b32 v2, v105, v2, 2 bitop3:0x36
	v_lshl_or_b32 v111, v0, 4, v4
	v_lshlrev_b32_e32 v0, 2, v105
	v_cmp_ge_i32_e32 vcc, s0, v107
	v_cmp_le_i32_e64 s[0:1], s7, v108
	v_lshl_or_b32 v109, v3, 4, v4
	v_lshl_or_b32 v110, v2, 4, v4
	v_sub_u32_e32 v65, v0, v66
	s_and_b64 s[0:1], vcc, s[0:1]
	s_and_saveexec_b64 s[12:13], s[38:39]
	s_xor_b64 s[78:79], exec, s[12:13]
	s_cbranch_execz .LBB0_275
	v_mov_b32_e32 v14, v1
	v_mov_b32_e32 v15, v1
	v_mov_b32_e32 v0, v1
	v_mov_b32_e32 v2, v1
	v_mov_b32_e32 v3, v1
	v_mov_b32_e32 v4, v1
	v_mov_b32_e32 v5, v1
	v_mov_b32_e32 v6, v1
	v_mov_b32_e32 v7, v1
	v_mov_b32_e32 v8, v1
	v_mov_b32_e32 v9, v1
	v_mov_b32_e32 v10, v1
	v_mov_b32_e32 v11, v1
	v_mov_b32_e32 v12, v1
	v_mov_b32_e32 v13, v1
	v_mov_b64_e32 v[30:31], v[14:15]
	v_mov_b64_e32 v[46:47], v[14:15]
	v_mov_b32_e32 v102, 0xf149f2ca
	v_mov_b32_e32 v112, 0
	v_mov_b64_e32 v[28:29], v[12:13]
	v_mov_b64_e32 v[26:27], v[10:11]
	v_mov_b64_e32 v[24:25], v[8:9]
	v_mov_b64_e32 v[22:23], v[6:7]
	v_mov_b64_e32 v[20:21], v[4:5]
	v_mov_b64_e32 v[18:19], v[2:3]
	v_mov_b64_e32 v[16:17], v[0:1]
	v_mov_b64_e32 v[44:45], v[12:13]
	v_mov_b64_e32 v[42:43], v[10:11]
	v_mov_b64_e32 v[40:41], v[8:9]
	v_mov_b64_e32 v[38:39], v[6:7]
	v_mov_b64_e32 v[36:37], v[4:5]
	v_mov_b64_e32 v[34:35], v[2:3]
	v_mov_b64_e32 v[32:33], v[0:1]
	s_and_saveexec_b64 s[80:81], s[0:1]
	s_cbranch_execz .LBB0_274
; #define MFMA32(a, b, c) __builtin_amdgcn_mfma_f32_32x32x16_bf16((a), (b), (c), 0, 0, 0)
; template <int MODE, int NQ, int TS, bool FAST = false> ...
;     ...
;   auto QK = [&](int slot) {
;     const char* kb_ = lds + slot * 16384;
; #pragma unroll
;     for (int nq = 0; nq < NQ; ++nq)
; #pragma unroll
;       for (int r = 0; r < 16; ++r) { s[nq][0][r] = 0.f; s[nq][1][r] = 0.f; }
; #pragma unroll
;     for (int ks = 0; ks < 4; ++ks) {
;       const bf16x8 k0 = *(const bf16x8*)(kb_ + kfo4[ks]), k1 = *(const bf16x8*)(kb_ + kfo4[ks] + 4096);
; #pragma unroll
;       for (int nq = 0; nq < NQ; ++nq) { s[nq][0] = MFMA32(k0, qf[nq][ks], s[nq][0]); s[nq][1] = MFMA32(k1, qf[nq][ks], s[nq][1]); }
;     }
;   };
;   auto SM = [&](int kt) {
; #pragma unroll
;     for (int nq = 0; nq < NQ; ++nq) {
;       f32x16& s0 = s[nq][0]; f32x16& s1 = s[nq][1];
;       float mx = -1e30f;
;       if (MODE == 1) {
;       } else if (MODE == 0 || MODE == 3) {
;         const float* tb = (const float*)(lds + TAB_OFF) + (kt * 64 + 4 * hh - (q0w + 32 * nq + r32) + TAB_ZERO);
; #pragma unroll
;         for (int r = 0; r < 16; ++r) {
;           const float va = fmaf(s0[r], C2, tb[(r & 3) + 8 * (r >> 2)]), vb = fmaf(s1[r], C2, tb[(r & 3) + 8 * (r >> 2) + 32]);
;           s0[r] = va; s1[r] = vb; mx = fmaxf(mx, fmaxf(va, vb));
;         }
;       } else {
;         const float* tb = (const float*)(lds + TAB_OFF) + (wave & 3) * 512 + (kt * 64 + 4 * hh - (q0w + 32 * nq + r32) + 256);
; #pragma unroll
;         for (int r = 0; r < 16; ++r) {
;           const float va = fmaf(s0[r], C2, tb[(r & 3) + 8 * (r >> 2)]), vb = fmaf(s1[r], C2, tb[(r & 3) + 8 * (r >> 2) + 32]);
;           s0[r] = va; s1[r] = vb; mx = fmaxf(mx, fmaxf(va, vb));
;         }
;       }
;       float mn;
;       if (MODE == 1) {
;         mn = sink2;
;       } else {
;         if (__any(mx > m2[nq] + 8.f)) {
;           mx = fmaxf(mx, __shfl_xor(mx, 32));
;           mn = fmaxf(m2[nq], mx);
;           const float alpha = __builtin_amdgcn_exp2f(m2[nq] - mn);
;           l[nq] *= alpha;
; #pragma unroll
;           for (int r = 0; r < 16; ++r) { o[nq][0][r] *= alpha; o[nq][1][r] *= alpha; }
;           m2[nq] = mn;
;         }
;         mn = m2[nq];
	ds_read_b128 v[2:5], v111
	ds_read_b128 v[18:21], v111 offset:4096
	ds_read_b128 v[34:37], v110
	ds_read_b128 v[38:41], v110 offset:4096
	v_lshlrev_b32_e32 v0, 2, v65
	v_lshl_add_u32 v50, s7, 2, v0
	s_waitcnt lgkmcnt(0)
	v_mfma_f32_32x32x16_bf16 v[2:17], v[2:5], v[80:83], 0
	v_mov_b32_e32 v102, 0xf149f2ca
	v_mfma_f32_32x32x16_bf16 v[18:33], v[18:21], v[80:83], 0
	v_mfma_f32_32x32x16_bf16 v[2:17], v[34:37], v[84:87], v[2:17]
	v_mfma_f32_32x32x16_bf16 v[18:33], v[38:41], v[84:87], v[18:33]
	ds_read_b128 v[34:37], v109
	ds_read_b128 v[38:41], v109 offset:4096
	s_waitcnt lgkmcnt(1)
	v_mfma_f32_32x32x16_bf16 v[2:17], v[34:37], v[88:91], v[2:17]
	s_waitcnt lgkmcnt(0)
	v_mfma_f32_32x32x16_bf16 v[18:33], v[38:41], v[88:91], v[18:33]
	ds_read_b128 v[34:37], v97
	ds_read_b128 v[38:41], v97 offset:4096
	s_waitcnt lgkmcnt(1)
	v_mfma_f32_32x32x16_bf16 v[2:17], v[34:37], v[92:95], v[2:17]
	v_add_u32_e32 v148, 0x18500, v50
	ds_read2_b32 v[116:117], v148 offset0:0 offset1:1
	ds_read2_b32 v[118:119], v148 offset0:32 offset1:33
	ds_read2_b32 v[120:121], v148 offset0:2 offset1:3
	ds_read2_b32 v[122:123], v148 offset0:34 offset1:35
	ds_read2_b32 v[124:125], v148 offset0:8 offset1:9
	ds_read2_b32 v[126:127], v148 offset0:40 offset1:41
	ds_read2_b32 v[128:129], v148 offset0:10 offset1:11
	ds_read2_b32 v[130:131], v148 offset0:42 offset1:43
	ds_read2_b32 v[132:133], v148 offset0:16 offset1:17
	ds_read2_b32 v[134:135], v148 offset0:48 offset1:49
	ds_read2_b32 v[136:137], v148 offset0:18 offset1:19
	ds_read2_b32 v[138:139], v148 offset0:50 offset1:51
	ds_read2_b32 v[140:141], v148 offset0:24 offset1:25
	ds_read2_b32 v[142:143], v148 offset0:56 offset1:57
	ds_read2_b32 v[144:145], v148 offset0:26 offset1:27
	ds_read2_b32 v[146:147], v148 offset0:58 offset1:59
	s_waitcnt lgkmcnt(15)
	v_mfma_f32_32x32x16_bf16 v[18:33], v[38:41], v[92:95], v[18:33]
	s_waitcnt lgkmcnt(0)
	s_nop 9
	v_fmamk_f32 v0, v2, 0x3e38aa3b, v116
	v_fmamk_f32 v35, v3, 0x3e38aa3b, v117
	s_waitcnt lgkmcnt(0)
	v_fmamk_f32 v34, v18, 0x3e38aa3b, v118
	v_fmamk_f32 v37, v19, 0x3e38aa3b, v119
	v_max_f32_e32 v2, v0, v34
	v_max_f32_e32 v3, v35, v37
	v_max3_f32 v18, v2, v102, v3
	s_waitcnt lgkmcnt(0)
	v_fmamk_f32 v2, v4, 0x3e38aa3b, v120
	v_fmamk_f32 v3, v5, 0x3e38aa3b, v121
	s_waitcnt lgkmcnt(0)
	v_fmamk_f32 v38, v20, 0x3e38aa3b, v122
	v_fmamk_f32 v39, v21, 0x3e38aa3b, v123
	v_max_f32_e32 v4, v2, v38
	v_max_f32_e32 v5, v3, v39
	v_max3_f32 v18, v18, v4, v5
	s_waitcnt lgkmcnt(0)
	v_fmamk_f32 v4, v6, 0x3e38aa3b, v124
	v_fmamk_f32 v5, v7, 0x3e38aa3b, v125
	s_waitcnt lgkmcnt(0)
	v_fmamk_f32 v36, v22, 0x3e38aa3b, v126
	v_fmamk_f32 v41, v23, 0x3e38aa3b, v127
	v_max_f32_e32 v6, v4, v36
	v_max_f32_e32 v7, v5, v41
	v_max3_f32 v18, v18, v6, v7
	s_waitcnt lgkmcnt(0)
	v_fmamk_f32 v6, v8, 0x3e38aa3b, v128
	v_fmamk_f32 v7, v9, 0x3e38aa3b, v129
	s_waitcnt lgkmcnt(0)
	v_fmamk_f32 v42, v24, 0x3e38aa3b, v130
	v_fmamk_f32 v43, v25, 0x3e38aa3b, v131
	v_max_f32_e32 v8, v6, v42
	v_max_f32_e32 v9, v7, v43
	v_max3_f32 v18, v18, v8, v9
	s_waitcnt lgkmcnt(0)
	v_fmamk_f32 v8, v10, 0x3e38aa3b, v132
	v_fmamk_f32 v9, v11, 0x3e38aa3b, v133
	s_waitcnt lgkmcnt(0)
	v_fmamk_f32 v40, v26, 0x3e38aa3b, v134
	v_fmamk_f32 v45, v27, 0x3e38aa3b, v135
	v_max_f32_e32 v10, v8, v40
	v_max_f32_e32 v11, v9, v45
	v_max3_f32 v18, v18, v10, v11
	s_waitcnt lgkmcnt(0)
	v_fmamk_f32 v10, v12, 0x3e38aa3b, v136
	v_fmamk_f32 v11, v13, 0x3e38aa3b, v137
	s_waitcnt lgkmcnt(0)
	v_fmamk_f32 v46, v28, 0x3e38aa3b, v138
	v_fmamk_f32 v47, v29, 0x3e38aa3b, v139
	v_max_f32_e32 v12, v10, v46
	v_max_f32_e32 v13, v11, v47
	v_max3_f32 v18, v18, v12, v13
	s_waitcnt lgkmcnt(0)
	v_fmamk_f32 v12, v14, 0x3e38aa3b, v140
	v_fmamk_f32 v13, v15, 0x3e38aa3b, v141
	s_waitcnt lgkmcnt(0)
	v_fmamk_f32 v44, v30, 0x3e38aa3b, v142
	v_fmamk_f32 v49, v31, 0x3e38aa3b, v143
	v_max_f32_e32 v14, v12, v44
	v_max_f32_e32 v15, v13, v49
	v_max3_f32 v18, v18, v14, v15
	s_waitcnt lgkmcnt(0)
	v_fmamk_f32 v14, v16, 0x3e38aa3b, v144
	v_fmamk_f32 v15, v17, 0x3e38aa3b, v145
	s_waitcnt lgkmcnt(0)
	v_fmamk_f32 v32, v32, 0x3e38aa3b, v146
	v_fmamk_f32 v51, v33, 0x3e38aa3b, v147
	v_max_f32_e32 v16, v14, v32
	v_max_f32_e32 v17, v15, v51
	v_max3_f32 v16, v18, v16, v17
	v_cmp_gt_f32_e32 vcc, v16, v102
	s_cbranch_vccz .LBB0_272
	v_xor_b32_e32 v17, 32, v223
	v_cmp_lt_i32_e32 vcc, v17, v225
	s_nop 1
	v_cndmask_b32_e32 v17, v223, v17, vcc
	v_lshlrev_b32_e32 v17, 2, v17
	ds_bpermute_b32 v17, v17, v16
	s_waitcnt lgkmcnt(0)
	v_max3_f32 v102, v16, v17, s25
	v_sub_f32_e32 v16, 0xf149f2ca, v102
	v_exp_f32_e32 v16, v16
	s_nop 0
	v_mul_f32_e32 v16, 0, v16
	s_branch .LBB0_273
